# ffn_fixup inner loop hand-written: the loads of all (up to 3) items of a thread are issued first instead of three serialized load waits per item
# baseline (speedup 1.0000x reference)
.LBB0_1039:
	s_and_b32 s6, s65, 15
	s_cmp_eq_u32 s6, 0
	s_cbranch_scc1 .LBB0_1030
	s_and_saveexec_b64 s[6:7], s[4:5]
	s_cbranch_execz .LBB0_1029
	s_mul_i32 s14, s65, 0x5800
	v_readlane_b32 s8, v254, 11
	s_mul_hi_i32 s11, s65, 0x5800
	v_readlane_b32 s9, v254, 12
	s_add_u32 s8, s8, s14
	s_addc_u32 s9, s9, s11
	v_readlane_b32 s16, v254, 13
	v_readlane_b32 s17, v254, 14
	s_add_u32 s10, s16, s14
	s_addc_u32 s11, s17, s11
	s_load_dwordx4 s[16:19], s[0:1], 0x68
	s_add_i32 s15, s65, -1
	s_addk_i32 s14, 0xa800
	v_readlane_b32 s20, v254, 9
	s_mul_hi_i32 s15, s15, 0x5800
	v_readlane_b32 s21, v254, 10
	s_add_u32 s29, s20, s14
	s_addc_u32 s30, s21, s15
	s_waitcnt lgkmcnt(0)
	s_add_u32 s14, s16, s25
	s_addc_u32 s15, s17, s24
	s_add_u32 s16, s18, s27
	s_addc_u32 s17, s19, s26
	s_add_u32 s31, s29, 0x2c00
	s_addc_u32 s42, s30, 0
	s_add_u32 s18, s14, 0x2c00
	s_addc_u32 s19, s15, 0
	s_add_u32 s20, s14, 0x5800
	s_addc_u32 s21, s15, 0
	s_lshl_b32 s44, s65, 8
	s_waitcnt vmcnt(0)
	s_mov_b32 s62, s29
	s_mov_b32 s63, s30
	v_cmp_gt_u32_e32 vcc, 0x180, v0
	s_and_saveexec_b64 s[100:101], vcc
	s_cbranch_execz .Lmy_fx_l2
	v_add_u32_e32 v125, 1024, v0
	v_cmp_lt_u32_e32 vcc, 0x2bf, v125
	v_cndmask_b32_e64 v122, 0, 1, vcc
	v_mov_b32_e32 v124, 0x2c0
	v_cndmask_b32_e32 v124, 0, v124, vcc
	v_sub_u32_e32 v125, v125, v124
	v_lshlrev_b32_e32 v120, 2, v125
	v_mov_b32_e32 v121, 0
	v_lshlrev_b32_e32 v124, 4, v125
	v_mov_b32_e32 v123, 0x2c00
	v_cndmask_b32_e32 v123, 0, v123, vcc
	v_add_u32_e32 v123, v124, v123
	v_mov_b32_e32 v158, s31
	v_mov_b32_e32 v159, s42
	v_mov_b32_e32 v125, s8
	v_cndmask_b32_e32 v158, v158, v125, vcc
	v_mov_b32_e32 v125, s9
	v_cndmask_b32_e32 v159, v159, v125, vcc
	v_mov_b32_e32 v125, 0
	v_lshl_add_u64 v[158:159], v[158:159], 0, v[124:125]
	global_load_dwordx4 v[138:141], v123, s[62:63]
	global_load_dwordx4 v[142:145], v124, s[16:17]
	global_load_dwordx4 v[146:149], v124, s[14:15]
	global_load_dwordx4 v[134:137], v[158:159], off
	global_load_dwordx4 v[130:133], v123, s[8:9]
	global_load_dwordx4 v[126:129], v123, s[10:11]
	global_load_dwordx4 v[150:153], v124, s[18:19]
	global_load_dwordx4 v[154:157], v124, s[20:21]
.Lmy_fx_l2:
	s_or_b64 exec, exec, s[100:101]
	v_mov_b32_e32 v45, v0
	v_cmp_lt_u32_e32 vcc, 0x2bf, v45
	v_cndmask_b32_e64 v42, 0, 1, vcc
	v_mov_b32_e32 v44, 0x2c0
	v_cndmask_b32_e32 v44, 0, v44, vcc
	v_sub_u32_e32 v45, v45, v44
	v_lshlrev_b32_e32 v40, 2, v45
	v_mov_b32_e32 v41, 0
	v_lshlrev_b32_e32 v44, 4, v45
	v_mov_b32_e32 v43, 0x2c00
	v_cndmask_b32_e32 v43, 0, v43, vcc
	v_add_u32_e32 v43, v44, v43
	v_mov_b32_e32 v78, s31
	v_mov_b32_e32 v79, s42
	v_mov_b32_e32 v45, s8
	v_cndmask_b32_e32 v78, v78, v45, vcc
	v_mov_b32_e32 v45, s9
	v_cndmask_b32_e32 v79, v79, v45, vcc
	v_mov_b32_e32 v45, 0
	v_lshl_add_u64 v[78:79], v[78:79], 0, v[44:45]
	global_load_dwordx4 v[58:61], v43, s[62:63]
	global_load_dwordx4 v[62:65], v44, s[16:17]
	global_load_dwordx4 v[66:69], v44, s[14:15]
	global_load_dwordx4 v[54:57], v[78:79], off
	global_load_dwordx4 v[50:53], v43, s[8:9]
	global_load_dwordx4 v[46:49], v43, s[10:11]
	global_load_dwordx4 v[70:73], v44, s[18:19]
	global_load_dwordx4 v[74:77], v44, s[20:21]
	v_add_u32_e32 v85, 512, v0
	v_cmp_lt_u32_e32 vcc, 0x2bf, v85
	v_cndmask_b32_e64 v82, 0, 1, vcc
	v_mov_b32_e32 v84, 0x2c0
	v_cndmask_b32_e32 v84, 0, v84, vcc
	v_sub_u32_e32 v85, v85, v84
	v_lshlrev_b32_e32 v80, 2, v85
	v_mov_b32_e32 v81, 0
	v_lshlrev_b32_e32 v84, 4, v85
	v_mov_b32_e32 v83, 0x2c00
	v_cndmask_b32_e32 v83, 0, v83, vcc
	v_add_u32_e32 v83, v84, v83
	v_mov_b32_e32 v118, s31
	v_mov_b32_e32 v119, s42
	v_mov_b32_e32 v85, s8
	v_cndmask_b32_e32 v118, v118, v85, vcc
	v_mov_b32_e32 v85, s9
	v_cndmask_b32_e32 v119, v119, v85, vcc
	v_mov_b32_e32 v85, 0
	v_lshl_add_u64 v[118:119], v[118:119], 0, v[84:85]
	global_load_dwordx4 v[98:101], v83, s[62:63]
	global_load_dwordx4 v[102:105], v84, s[16:17]
	global_load_dwordx4 v[106:109], v84, s[14:15]
	global_load_dwordx4 v[94:97], v[118:119], off
	global_load_dwordx4 v[90:93], v83, s[8:9]
	global_load_dwordx4 v[86:89], v83, s[10:11]
	global_load_dwordx4 v[110:113], v84, s[18:19]
	global_load_dwordx4 v[114:117], v84, s[20:21]
	s_waitcnt vmcnt(8)
	v_pk_fma_f32 v[62:63], v[58:59], v[66:67], v[62:63]
	v_pk_fma_f32 v[64:65], v[60:61], v[68:69], v[64:65]
	v_pk_fma_f32 v[70:71], v[54:55], v[70:71], v[62:63]
	v_pk_fma_f32 v[72:73], v[56:57], v[72:73], v[64:65]
	v_pk_fma_f32 v[52:53], v[52:53], v[76:77], v[72:73]
	v_pk_fma_f32 v[50:51], v[50:51], v[74:75], v[70:71]
	v_pk_mul_f32 v[74:75], v[52:53], v[52:53]
	v_pk_mul_f32 v[76:77], v[50:51], v[50:51]
	v_mov_b64_e32 v[70:71], s[88:89]
	v_pk_fma_f32 v[76:77], v[76:77], s[96:97], v[70:71] op_sel_hi:[1,0,0] neg_lo:[1,0,0] neg_hi:[1,0,0]
	v_pk_fma_f32 v[74:75], v[74:75], s[96:97], v[70:71] op_sel_hi:[1,0,0] neg_lo:[1,0,0] neg_hi:[1,0,0]
	v_pk_mul_f32 v[76:77], v[50:51], v[76:77]
	v_pk_mul_f32 v[74:75], v[52:53], v[74:75]
	v_exp_f32_e32 v76, v76
	v_exp_f32_e32 v77, v77
	v_exp_f32_e32 v74, v74
	v_exp_f32_e32 v75, v75
	v_pk_add_f32 v[76:77], v[76:77], 1.0 op_sel_hi:[1,0]
	s_nop 0
	v_rcp_f32_e32 v76, v76
	v_pk_add_f32 v[74:75], v[74:75], 1.0 op_sel_hi:[1,0]
	v_rcp_f32_e32 v77, v77
	v_rcp_f32_e32 v74, v74
	v_rcp_f32_e32 v75, v75
	v_pk_mul_f32 v[50:51], v[50:51], v[76:77]
	s_nop 0
	v_pk_mul_f32 v[46:47], v[46:47], v[50:51]
	v_pk_mul_f32 v[52:53], v[52:53], v[74:75]
	v_cvt_pk_bf16_f32 v46, v46, v47
	v_add_u32_e32 v45, s44, v42
	v_pk_mul_f32 v[48:49], v[48:49], v[52:53]
	s_nop 0
	v_cvt_pk_bf16_f32 v47, v48, v49
	v_mov_b64_e32 v[48:49], s[60:61]
	v_mad_i64_i32 v[48:49], s[50:51], v45, s3, v[48:49]
	v_lshl_add_u64 v[48:49], v[40:41], 1, v[48:49]
	global_store_dwordx2 v[48:49], v[46:47], off
	s_waitcnt vmcnt(1)
	v_pk_fma_f32 v[102:103], v[98:99], v[106:107], v[102:103]
	v_pk_fma_f32 v[104:105], v[100:101], v[108:109], v[104:105]
	v_pk_fma_f32 v[110:111], v[94:95], v[110:111], v[102:103]
	v_pk_fma_f32 v[112:113], v[96:97], v[112:113], v[104:105]
	v_pk_fma_f32 v[92:93], v[92:93], v[116:117], v[112:113]
	v_pk_fma_f32 v[90:91], v[90:91], v[114:115], v[110:111]
	v_pk_mul_f32 v[114:115], v[92:93], v[92:93]
	v_pk_mul_f32 v[116:117], v[90:91], v[90:91]
	v_mov_b64_e32 v[110:111], s[88:89]
	v_pk_fma_f32 v[116:117], v[116:117], s[96:97], v[110:111] op_sel_hi:[1,0,0] neg_lo:[1,0,0] neg_hi:[1,0,0]
	v_pk_fma_f32 v[114:115], v[114:115], s[96:97], v[110:111] op_sel_hi:[1,0,0] neg_lo:[1,0,0] neg_hi:[1,0,0]
	v_pk_mul_f32 v[116:117], v[90:91], v[116:117]
	v_pk_mul_f32 v[114:115], v[92:93], v[114:115]
	v_exp_f32_e32 v116, v116
	v_exp_f32_e32 v117, v117
	v_exp_f32_e32 v114, v114
	v_exp_f32_e32 v115, v115
	v_pk_add_f32 v[116:117], v[116:117], 1.0 op_sel_hi:[1,0]
	s_nop 0
	v_rcp_f32_e32 v116, v116
	v_pk_add_f32 v[114:115], v[114:115], 1.0 op_sel_hi:[1,0]
	v_rcp_f32_e32 v117, v117
	v_rcp_f32_e32 v114, v114
	v_rcp_f32_e32 v115, v115
	v_pk_mul_f32 v[90:91], v[90:91], v[116:117]
	s_nop 0
	v_pk_mul_f32 v[86:87], v[86:87], v[90:91]
	v_pk_mul_f32 v[92:93], v[92:93], v[114:115]
	v_cvt_pk_bf16_f32 v86, v86, v87
	v_add_u32_e32 v85, s44, v82
	v_pk_mul_f32 v[88:89], v[88:89], v[92:93]
	s_nop 0
	v_cvt_pk_bf16_f32 v87, v88, v89
	v_mov_b64_e32 v[88:89], s[60:61]
	v_mad_i64_i32 v[88:89], s[50:51], v85, s3, v[88:89]
	v_lshl_add_u64 v[88:89], v[80:81], 1, v[88:89]
	global_store_dwordx2 v[88:89], v[86:87], off
	v_cmp_gt_u32_e32 vcc, 0x180, v0
	s_and_saveexec_b64 s[100:101], vcc
	s_cbranch_execz .Lmy_fx_c2
	v_pk_fma_f32 v[142:143], v[138:139], v[146:147], v[142:143]
	v_pk_fma_f32 v[144:145], v[140:141], v[148:149], v[144:145]
	v_pk_fma_f32 v[150:151], v[134:135], v[150:151], v[142:143]
	v_pk_fma_f32 v[152:153], v[136:137], v[152:153], v[144:145]
	v_pk_fma_f32 v[132:133], v[132:133], v[156:157], v[152:153]
	v_pk_fma_f32 v[130:131], v[130:131], v[154:155], v[150:151]
	v_pk_mul_f32 v[154:155], v[132:133], v[132:133]
	v_pk_mul_f32 v[156:157], v[130:131], v[130:131]
	v_mov_b64_e32 v[150:151], s[88:89]
	v_pk_fma_f32 v[156:157], v[156:157], s[96:97], v[150:151] op_sel_hi:[1,0,0] neg_lo:[1,0,0] neg_hi:[1,0,0]
	v_pk_fma_f32 v[154:155], v[154:155], s[96:97], v[150:151] op_sel_hi:[1,0,0] neg_lo:[1,0,0] neg_hi:[1,0,0]
	v_pk_mul_f32 v[156:157], v[130:131], v[156:157]
	v_pk_mul_f32 v[154:155], v[132:133], v[154:155]
	v_exp_f32_e32 v156, v156
	v_exp_f32_e32 v157, v157
	v_exp_f32_e32 v154, v154
	v_exp_f32_e32 v155, v155
	v_pk_add_f32 v[156:157], v[156:157], 1.0 op_sel_hi:[1,0]
	s_nop 0
	v_rcp_f32_e32 v156, v156
	v_pk_add_f32 v[154:155], v[154:155], 1.0 op_sel_hi:[1,0]
	v_rcp_f32_e32 v157, v157
	v_rcp_f32_e32 v154, v154
	v_rcp_f32_e32 v155, v155
	v_pk_mul_f32 v[130:131], v[130:131], v[156:157]
	s_nop 0
	v_pk_mul_f32 v[126:127], v[126:127], v[130:131]
	v_pk_mul_f32 v[132:133], v[132:133], v[154:155]
	v_cvt_pk_bf16_f32 v126, v126, v127
	v_add_u32_e32 v125, s44, v122
	v_pk_mul_f32 v[128:129], v[128:129], v[132:133]
	s_nop 0
	v_cvt_pk_bf16_f32 v127, v128, v129
	v_mov_b64_e32 v[128:129], s[60:61]
	v_mad_i64_i32 v[128:129], s[50:51], v125, s3, v[128:129]
	v_lshl_add_u64 v[128:129], v[120:121], 1, v[128:129]
	global_store_dwordx2 v[128:129], v[126:127], off
.Lmy_fx_c2:
	s_or_b64 exec, exec, s[100:101]
	s_branch .LBB0_1029
